# attention: waves 4-7 stage the next K/V tile before computing the current one (waves 0-3 after)
# speedup vs baseline: 1.0342x; 1.0155x over previous
; #define LAS __attribute__((address_space(3)))
; __device__ __forceinline__ void unit(unsigned char* ws, LAS unsigned char* lds, int b, int h, int mp, int qb, const int tid_in) {
;     ...
;     for (int kt = 0; kt < NT; ++kt) {
;         LAS bf16_t* KS = KV0 + (kt & 1) * KVB; LAS bf16_t* VT = KS + 64 * KP;
;         const int k0 = kt * 64;
;         if (k0 <= qw0 + 31) {
;     ...
;         if (kt + 1 < NT) { FA3_STAGE((kt + 1) & 1); kA = kB; vA0 = vB0; vA1 = vB1;
;             if (kt + 3 < NT) { const size_t off = (size_t)(kt + 3) * 64 * 512; kB = *(const u32x4*)(kg + off); vB0 = *(const u32x4*)(vg + off); vB1 = *(const u32x4*)(vg + off + 512); } }
;         __syncthreads();
.LBB0_182:
	s_cmp_ge_u32 s3, 4
	s_cbranch_scc1 .LBB0_196

; #define LAS __attribute__((address_space(3)))
; __device__ __forceinline__ void unit(unsigned char* ws, LAS unsigned char* lds, int b, int h, int mp, int qb, const int tid_in) {
;     ...
;     for (int kt = 0; kt < NT; ++kt) {
;         LAS bf16_t* KS = KV0 + (kt & 1) * KVB; LAS bf16_t* VT = KS + 64 * KP;
;         const int k0 = kt * 64;
;         if (k0 <= qw0 + 31) {
;         f32x4 s[2][4];
; #pragma unroll
;         for (int jt = 0; jt < 4; ++jt) { const bf16x8 kf0 = *(const LAS bf16x8*)(KS + (16 * jt + fr) * KP + 8 * fq), kf1 = *(const LAS bf16x8*)(KS + (16 * jt + fr) * KP + 32 + 8 * fq);
; #pragma unroll
;             for (int g = 0; g < 2; ++g) { const float nm = -m[g]; s[g][jt] = __builtin_amdgcn_mfma_f32_16x16x32_bf16(kf0, qf[g][0], (f32x4){nm, nm, nm, nm}, 0, 0, 0); s[g][jt] = __builtin_amdgcn_mfma_f32_16x16x32_bf16(kf1, qf[g][1], s[g][jt], 0, 0, 0); } }
;         const bool nearb = (qw0 - (k0 + 63) < 113);
.LBB0_198:
	s_add_i32 s68, s68, 1
	s_add_i32 s21, s79, s68
	s_sub_i32 s81, s81, 64
	s_add_i32 s69, s69, 64
	v_lshl_add_u64 v[160:161], v[160:161], 0, s[40:41]
	v_lshl_add_u64 v[162:163], v[162:163], 0, s[40:41]
	s_cmp_eq_u32 s21, 6
	v_add_u32_e32 v176, 0xffffff00, v176
	s_waitcnt lgkmcnt(0)
	s_barrier
	s_cbranch_scc0 .LBB0_182
	s_bitcmp1_b32 s68, 0
	s_cselect_b32 s22, 0, 0x6c00
	s_lshl_b32 s21, s68, 6
	s_addk_i32 s21, 0xff40
	s_cmp_gt_i32 s21, s76
	s_cbranch_scc1 .LBB0_171
	s_waitcnt vmcnt(2)
	v_add_u32_e32 v114, s22, v173
	v_lshl_add_u32 v0, v169, 1, v114
	ds_read_b128 v[90:93], v0
	ds_read_b128 v[98:101], v0 offset:64
	v_xor_b32_e32 v116, 0x80000000, v175
	v_mov_b32_e32 v117, v116
	s_waitcnt vmcnt(0)
	v_mov_b32_e32 v118, v116
	v_mov_b32_e32 v119, v116
	v_xor_b32_e32 v120, 0x80000000, v177
	v_mov_b32_e32 v121, v120
	v_mov_b32_e32 v122, v120
	s_waitcnt lgkmcnt(1)
	v_mfma_f32_16x16x32_bf16 v[94:97], v[90:93], v[82:85], v[116:119]
	v_mov_b32_e32 v123, v120
	s_sub_i32 s26, s71, s21
	s_cmpk_gt_i32 s26, 0x70
	s_waitcnt lgkmcnt(0)
	v_mfma_f32_16x16x32_bf16 v[102:105], v[98:101], v[78:81], v[94:97]
	ds_read_b128 v[110:113], v0 offset:2368
	s_cselect_b64 s[22:23], -1, 0
	s_cmpk_lt_i32 s26, 0x71
	ds_read_b128 v[94:97], v0 offset:2304
	v_mfma_f32_16x16x32_bf16 v[90:93], v[90:93], v[86:89], v[120:123]
	s_mov_b64 s[60:61], -1
	ds_read_b128 v[124:127], v0 offset:4672
	v_mfma_f32_16x16x32_bf16 v[90:93], v[98:101], v[74:77], v[90:93]
	s_waitcnt lgkmcnt(1)
	v_mfma_f32_16x16x32_bf16 v[98:101], v[94:97], v[82:85], v[116:119]
	v_mfma_f32_16x16x32_bf16 v[106:109], v[110:113], v[78:81], v[98:101]
	v_mfma_f32_16x16x32_bf16 v[94:97], v[94:97], v[86:89], v[120:123]
	s_nop 5
	ds_read_b128 v[98:101], v0 offset:4608
	v_mfma_f32_16x16x32_bf16 v[94:97], v[110:113], v[74:77], v[94:97]
	s_waitcnt lgkmcnt(0)
	v_mfma_f32_16x16x32_bf16 v[110:113], v[98:101], v[82:85], v[116:119]
	v_mfma_f32_16x16x32_bf16 v[98:101], v[98:101], v[86:89], v[120:123]
	v_mfma_f32_16x16x32_bf16 v[110:113], v[124:127], v[78:81], v[110:113]
	v_mfma_f32_16x16x32_bf16 v[98:101], v[124:127], v[74:77], v[98:101]
	ds_read_b128 v[124:127], v0 offset:6912
	s_waitcnt lgkmcnt(0)
	v_mfma_f32_16x16x32_bf16 v[82:85], v[124:127], v[82:85], v[116:119]
	s_nop 2
	ds_read_b128 v[116:119], v0 offset:6976
	s_waitcnt lgkmcnt(0)
	v_mfma_f32_16x16x32_bf16 v[78:81], v[116:119], v[78:81], v[82:85]
	v_mfma_f32_16x16x32_bf16 v[82:85], v[124:127], v[86:89], v[120:123]
	v_mfma_f32_16x16x32_bf16 v[74:77], v[116:119], v[74:77], v[82:85]
	s_cbranch_scc1 .LBB0_202
	s_mov_b64 s[60:61], 0
